# k14: k8 + ret chunk loop trims (dead zeroing, spos recompute, decay and qd factors hoisted out of the chunk loop)
# speedup vs baseline: 1.0039x; 1.0039x over previous
; __device__ void ret_phase(const Params& p, unsigned char* ldsb, int lj, int half) {
;     ...
;         const int xq = item & 7, yq = item >> 3, sl = yq & 3, bh = (yq >> 2) * 8 + xq, bl = bh >> 2, h = bh & 3;
;         const int bglob = half * 16 + bl;
;         const float l2gF = -fabsf(p.ret_log_decay[(lj * 2 + 0) * 4 + h]) * 1.4426950408889634f, l2gB = -fabsf(p.ret_log_decay[(lj * 2 + 1) * 4 + h]) * 1.4426950408889634f;
;         for (int pass = 0; pass < 2; ++pass) {
;             const int dir = 1 - pass;
;             const float lg = -fabsf(p.ret_log_decay[(lj * 2 + dir) * 4 + h]);
;             const float l2g = lg * 1.4426950408889634f;
;             const float Gc = __builtin_amdgcn_exp2f(64.0f * l2g);
;             float ge[8];
; #pragma unroll
;             for (int e = 0; e < 8; ++e) ge[e] = __builtin_amdgcn_exp2f((dir == 0 ? -(float)e : (float)e) * l2g);
;             f32x4 S[16];
; #pragma unroll
;             for (int i = 0; i < 16; ++i) S[i] = (f32x4){0.f, 0.f, 0.f, 0.f};
;             u32x4 sq[4], sk[4]; u32x4 sv[2]; u32x2 yold[4];
;             auto spos = [&](int c) -> int { return dir == 0 ? 64 * c : (c < 4 ? 192 - 64 * c : 2496 - 64 * c); };
;             auto lrow = [&](int s0) -> int { return s0 < 256 ? bl * 256 + s0 : 4096 + bl * 2048 + (s0 - 256); };
;             auto grow = [&](int s0) -> int { return s0 < 256 ? bglob * 256 + s0 : TCTX + bglob * 2048 + (s0 - 256); };
;             const unsigned vo_qk = (unsigned)(((tid0 >> 5) * 1024 + (tid0 & 31) * 8) * 2);
;             const unsigned vo_v = (unsigned)(((tid0 >> 4) * 2048 + (tid0 & 15) * 8) * 2);
;             const unsigned vo_y = (unsigned)((r0_ * 2048 + 4 * g0_) * 2);
;     ...
;                     for (int nt = 0; nt < 2; ++nt) { const int i = 32 * ih + 16 * nt + r; const int j0 = 16 * jb + 4 * g;
;                         float pv[4];
; #pragma unroll
;                         for (int jj = 0; jj < 4; ++jj) { const int df = j0 + jj - i;
;                             pv[jj] = sc[nt][jj] * __builtin_amdgcn_exp2f(df > 0 ? (float)df * l2gB : (float)(-df) * l2gF); }
.LBB0_377:
	s_ashr_i32 s1, s18, 2
	s_and_b32 s0, s18, 4
	s_and_b32 s1, s1, -8
	s_or_b32 s2, s1, s0
	s_and_b32 s3, s18, 3
	s_ashr_i32 s0, s2, 2
	s_or_b32 s76, s3, s30
	s_add_i32 s4, s0, s68
	s_lshl_b64 s[0:1], s[76:77], 2
	s_add_u32 s0, s54, s0
	s_addc_u32 s1, s55, s1
	global_load_dword v1, v0, s[0:1]
	s_lshl_b32 s31, s2, 6
	s_mov_b64 s[58:59], -1
	s_mov_b64 s[78:79], 0
	s_waitcnt vmcnt(0)
	v_mul_f32_e64 v189, |v1|, s95
	global_load_dword v1, v0, s[0:1] offset:16
	s_lshl_b32 s0, s3, 9
	s_add_u32 s44, s34, s0
	s_addc_u32 s80, s35, 0
	s_add_u32 s24, s40, s0
	s_addc_u32 s25, s41, 0
	s_lshl_b32 s3, s3, 10
	s_add_u32 s0, s48, s3
	s_addc_u32 s1, s49, 0
	s_lshl_b32 s5, s18, 5
	s_and_b32 s5, s5, 0x300
	s_add_u32 s0, s0, s5
	s_addc_u32 s1, s1, 0
	s_add_u32 s3, s38, s3
	s_addc_u32 s10, s39, 0
	s_add_u32 s11, s3, s5
	s_addc_u32 s10, s10, 0
	s_lshl_b32 s36, s4, 11
	s_lshl_b32 s50, s2, 9
	s_addk_i32 s36, 0x1f00
	s_lshl_b32 s64, s4, 8
	s_addk_i32 s50, 0xf00
	s_lshl_b64 s[2:3], s[16:17], 1
	s_add_u32 s28, s11, s2
	s_addc_u32 s29, s10, s3
	s_ashr_i32 s65, s64, 31
	s_lshl_b64 s[4:5], s[64:65], 12
	s_add_u32 s4, s11, s4
	s_addc_u32 s5, s10, s5
	s_add_u32 s2, s4, s2
	s_addc_u32 s3, s5, s3
	v_lshl_add_u64 v[164:165], s[2:3], 0, v[160:161]
	s_mov_b64 s[2:3], 0x30000
	v_lshl_add_u64 v[162:163], s[28:29], 0, v[160:161]
	s_mov_b32 s2, 0
	s_waitcnt vmcnt(0)
	v_mul_f32_e64 v190, |v1|, s95
	v_add_u32_e32 v108, s71, v187
	v_lshl_add_u32 v109, v188, 2, s70
	v_sub_u32_e32 v110, v109, v108
	v_add_u32_e32 v111, 0, v110
	v_sub_u32_e32 v112, 0, v111
	v_cmp_lt_i32_e32 vcc, 0, v111
	v_max_i32_e32 v111, v111, v112
	v_cvt_f32_u32_e32 v111, v111
	v_cndmask_b32_e32 v112, v189, v190, vcc
	v_mul_f32_e32 v111, v112, v111
	v_exp_f32_e32 v166, v111
	v_add_u32_e32 v111, 1, v110
	v_sub_u32_e32 v112, 0, v111
	v_cmp_lt_i32_e32 vcc, 0, v111
	v_max_i32_e32 v111, v111, v112
	v_cvt_f32_u32_e32 v111, v111
	v_cndmask_b32_e32 v112, v189, v190, vcc
	v_mul_f32_e32 v111, v112, v111
	v_exp_f32_e32 v167, v111
	v_add_u32_e32 v111, 2, v110
	v_sub_u32_e32 v112, 0, v111
	v_cmp_lt_i32_e32 vcc, 0, v111
	v_max_i32_e32 v111, v111, v112
	v_cvt_f32_u32_e32 v111, v111
	v_cndmask_b32_e32 v112, v189, v190, vcc
	v_mul_f32_e32 v111, v112, v111
	v_exp_f32_e32 v168, v111
	v_add_u32_e32 v111, 3, v110
	v_sub_u32_e32 v112, 0, v111
	v_cmp_lt_i32_e32 vcc, 0, v111
	v_max_i32_e32 v111, v111, v112
	v_cvt_f32_u32_e32 v111, v111
	v_cndmask_b32_e32 v112, v189, v190, vcc
	v_mul_f32_e32 v111, v112, v111
	v_exp_f32_e32 v169, v111
	v_add_u32_e32 v111, -16, v110
	v_sub_u32_e32 v112, 0, v111
	v_cmp_lt_i32_e32 vcc, 0, v111
	v_max_i32_e32 v111, v111, v112
	v_cvt_f32_u32_e32 v111, v111
	v_cndmask_b32_e32 v112, v189, v190, vcc
	v_mul_f32_e32 v111, v112, v111
	v_exp_f32_e32 v170, v111
	v_add_u32_e32 v111, -15, v110
	v_sub_u32_e32 v112, 0, v111
	v_cmp_lt_i32_e32 vcc, 0, v111
	v_max_i32_e32 v111, v111, v112
	v_cvt_f32_u32_e32 v111, v111
	v_cndmask_b32_e32 v112, v189, v190, vcc
	v_mul_f32_e32 v111, v112, v111
	v_exp_f32_e32 v171, v111
	v_add_u32_e32 v111, -14, v110
	v_sub_u32_e32 v112, 0, v111
	v_cmp_lt_i32_e32 vcc, 0, v111
	v_max_i32_e32 v111, v111, v112
	v_cvt_f32_u32_e32 v111, v111
	v_cndmask_b32_e32 v112, v189, v190, vcc
	v_mul_f32_e32 v111, v112, v111
	v_exp_f32_e32 v250, v111
	v_add_u32_e32 v111, -13, v110
	v_sub_u32_e32 v112, 0, v111
	v_cmp_lt_i32_e32 vcc, 0, v111
	v_max_i32_e32 v111, v111, v112
	v_cvt_f32_u32_e32 v111, v111
	v_cndmask_b32_e32 v112, v189, v190, vcc
	v_mul_f32_e32 v111, v112, v111
	v_exp_f32_e32 v251, v111
; __device__ void ret_phase(const Params& p, unsigned char* ldsb, int lj, int half) {
;     ...
;         const float l2gF = -fabsf(p.ret_log_decay[(lj * 2 + 0) * 4 + h]) * 1.4426950408889634f, l2gB = -fabsf(p.ret_log_decay[(lj * 2 + 1) * 4 + h]) * 1.4426950408889634f;
;         for (int pass = 0; pass < 2; ++pass) {
;             const int dir = 1 - pass;
;             const float lg = -fabsf(p.ret_log_decay[(lj * 2 + dir) * 4 + h]);
;             const float l2g = lg * 1.4426950408889634f;
;             const float Gc = __builtin_amdgcn_exp2f(64.0f * l2g);
;             float ge[8];
; #pragma unroll
;             for (int e = 0; e < 8; ++e) ge[e] = __builtin_amdgcn_exp2f((dir == 0 ? -(float)e : (float)e) * l2g);
;             f32x4 S[16];
; #pragma unroll
;             for (int i = 0; i < 16; ++i) S[i] = (f32x4){0.f, 0.f, 0.f, 0.f};
;             u32x4 sq[4], sk[4]; u32x4 sv[2]; u32x2 yold[4];
;             auto spos = [&](int c) -> int { return dir == 0 ? 64 * c : (c < 4 ? 192 - 64 * c : 2496 - 64 * c); };
;             auto lrow = [&](int s0) -> int { return s0 < 256 ? bl * 256 + s0 : 4096 + bl * 2048 + (s0 - 256); };
;             auto grow = [&](int s0) -> int { return s0 < 256 ? bglob * 256 + s0 : TCTX + bglob * 2048 + (s0 - 256); };
;             const unsigned vo_qk = (unsigned)(((tid0 >> 5) * 1024 + (tid0 & 31) * 8) * 2);
;             const unsigned vo_v = (unsigned)(((tid0 >> 4) * 2048 + (tid0 & 15) * 8) * 2);
;             const unsigned vo_y = (unsigned)((r0_ * 2048 + 4 * g0_) * 2);
;             auto issueQ = [&](int c) { const char* bq = (const char*)(Qg + (size_t)lrow(spos(c)) * 1024 + h * 256);
; #pragma unroll
;                 for (int k = 0; k < 4; ++k) sq[k] = *(const u32x4*)(bq + (size_t)k * 32768 + vo_qk); };
;             auto issueK = [&](int c) { const char* bk = (const char*)(Kg + (size_t)lrow(spos(c)) * 1024 + h * 256);
; #pragma unroll
;                 for (int k = 0; k < 4; ++k) sk[k] = *(const u32x4*)(bk + (size_t)k * 32768 + vo_qk); };
;             auto issueVY = [&](int c) { const char* bv = (const char*)(Vg + (size_t)lrow(spos(c)) * 2048 + h * 512 + sl * 128);
; #pragma unroll
;                 for (int k = 0; k < 2; ++k) sv[k] = *(const u32x4*)(bv + (size_t)k * 131072 + vo_v);
;                 if (pass == 1) { const char* by = (const char*)(Y + (size_t)grow(spos(c)) * 2048 + h * 512 + sl * 128 + 16 * w);
; #pragma unroll
.LBB0_378:
	s_sub_i32 s2, s76, s2
	s_ashr_i32 s3, s2, 31
	s_xor_b64 s[66:67], s[78:79], -1
	s_lshl_b64 s[2:3], s[2:3], 2
	s_add_u32 s2, s54, s2
	s_addc_u32 s3, s55, s3
	global_load_dword v1, v0, s[2:3] offset:16
	s_and_b64 s[2:3], s[78:79], exec
	s_cselect_b32 s2, 0, 0xc0
	s_or_b32 s2, s2, s31
	s_ashr_i32 s3, s2, 31
	s_lshl_b64 s[4:5], s[2:3], 11
	s_add_u32 s10, s44, s4
	s_addc_u32 s11, s80, s5
	v_lshl_add_u64 v[2:3], s[10:11], 0, v[156:157]
	s_waitcnt vmcnt(3)
	v_add_co_u32_e32 v8, vcc, s47, v2
	s_add_u32 s4, s24, s4
	s_nop 0
	v_addc_co_u32_e32 v9, vcc, 0, v3, vcc
	v_add_co_u32_e32 v12, vcc, s45, v2
	global_load_dwordx4 v[4:7], v[2:3], off
	s_nop 0
	global_load_dwordx4 v[8:11], v[8:9], off
	v_addc_co_u32_e32 v13, vcc, 0, v3, vcc
	v_add_co_u32_e32 v2, vcc, s46, v2
	s_addc_u32 s5, s25, s5
	s_nop 0
	v_addc_co_u32_e32 v3, vcc, 0, v3, vcc
	global_load_dwordx4 v[16:19], v[12:13], off
	global_load_dwordx4 v[24:27], v[2:3], off
	v_lshl_add_u64 v[2:3], s[4:5], 0, v[156:157]
	v_add_co_u32_e32 v20, vcc, s47, v2
	s_lshl_b64 s[2:3], s[2:3], 12
	s_nop 0
	v_addc_co_u32_e32 v21, vcc, 0, v3, vcc
	s_waitcnt vmcnt(6)
	v_add_co_u32_e32 v28, vcc, s45, v2
	global_load_dwordx4 v[12:15], v[2:3], off
	s_nop 0
	global_load_dwordx4 v[20:23], v[20:21], off
	v_addc_co_u32_e32 v29, vcc, 0, v3, vcc
	v_add_co_u32_e32 v2, vcc, s46, v2
	s_add_u32 s2, s0, s2
	s_nop 0
	v_addc_co_u32_e32 v3, vcc, 0, v3, vcc
	s_addc_u32 s3, s1, s3
	global_load_dwordx4 v[28:31], v[28:29], off
	s_nop 0
	global_load_dwordx4 v[48:51], v[2:3], off
	v_lshl_add_u64 v[2:3], s[2:3], 0, v[158:159]
	v_add_co_u32_e32 v36, vcc, 0x20000, v2
	s_nop 1
	v_addc_co_u32_e32 v37, vcc, 0, v3, vcc
	global_load_dwordx4 v[32:35], v[2:3], off
	global_load_dwordx4 v[52:55], v[36:37], off
	s_and_b64 vcc, exec, s[66:67]
	s_cbranch_vccnz .LBB0_380
	s_mov_b64 s[2:3], 0x30000
	v_lshl_add_u64 v[166:167], v[164:165], 0, s[84:85]
	v_lshl_add_u64 v[168:169], v[164:165], 0, s[82:83]
	v_lshl_add_u64 v[170:171], v[164:165], 0, s[2:3]
	global_load_dwordx2 v[136:137], v[164:165], off
	global_load_dwordx2 v[138:139], v[166:167], off
	global_load_dwordx2 v[140:141], v[168:169], off
	global_load_dwordx2 v[142:143], v[170:171], off
.LBB0_380:
	v_bfrev_b32_e32 v2, 1
	s_waitcnt vmcnt(10)
	v_mul_f32_e64 v191, |v1|, s95
	v_cndmask_b32_e64 v2, 0, v2, s[78:79]
	v_mul_f32_e32 v2, v2, v191
	v_exp_f32_e32 v192, v2
	v_cndmask_b32_e64 v2, v191, -v191, s[78:79]
	v_exp_f32_e32 v193, v2
	v_cndmask_b32_e64 v2, 2.0, -2.0, s[78:79]
	v_mul_f32_e32 v2, v2, v191
	v_exp_f32_e32 v194, v2
	v_mov_b32_e32 v2, 0x40400000
	v_mov_b32_e32 v3, 0xc0400000
	v_cndmask_b32_e64 v2, v2, v3, s[78:79]
	v_mul_f32_e32 v2, v2, v191
	v_exp_f32_e32 v195, v2
	v_cndmask_b32_e64 v2, 4.0, -4.0, s[78:79]
	v_mul_f32_e32 v2, v2, v191
	v_exp_f32_e32 v196, v2
	v_mov_b32_e32 v2, 0x40a00000
	v_cndmask_b32_e64 v2, v2, v220, s[78:79]
	v_mul_f32_e32 v1, 0x42800000, v191
	v_mul_f32_e32 v2, v2, v191
	v_exp_f32_e32 v197, v2
	v_cndmask_b32_e64 v2, v221, v222, s[78:79]
	v_exp_f32_e32 v172, v1
	v_cndmask_b32_e64 v1, v223, v224, s[78:79]
	v_mul_f32_e32 v2, v2, v191
	v_mul_f32_e32 v1, v1, v191
	v_exp_f32_e32 v198, v2
	v_exp_f32_e32 v199, v1
	v_add_u32_e32 v2, 1, v187
	v_sub_u32_e32 v3, 64, v187
	v_cndmask_b32_e64 v2, v3, v2, s[78:79]
	v_cvt_f32_i32_e32 v2, v2
	v_mul_f32_e32 v2, v191, v2
	v_exp_f32_e32 v252, v2
	v_add_u32_e32 v2, 17, v187
	v_sub_u32_e32 v3, 48, v187
	v_cndmask_b32_e64 v2, v3, v2, s[78:79]
	v_cvt_f32_i32_e32 v2, v2
	v_mul_f32_e32 v2, v191, v2
	v_exp_f32_e32 v253, v2
	v_add_u32_e32 v2, 33, v187
	v_sub_u32_e32 v3, 32, v187
	v_cndmask_b32_e64 v2, v3, v2, s[78:79]
	v_cvt_f32_i32_e32 v2, v2
	v_mul_f32_e32 v2, v191, v2
	v_exp_f32_e32 v209, v2
	v_add_u32_e32 v2, 49, v187
	v_sub_u32_e32 v3, 16, v187
	v_cndmask_b32_e64 v2, v3, v2, s[78:79]
	v_cvt_f32_i32_e32 v2, v2
	v_mul_f32_e32 v2, v191, v2
	v_exp_f32_e32 v225, v2
	v_mov_b32_e32 v2, v0
	v_mov_b32_e32 v3, v0
	v_mov_b32_e32 v1, v0
	v_mov_b64_e32 v[38:39], v[2:3]
	v_mov_b64_e32 v[62:63], v[2:3]
	v_mov_b64_e32 v[42:43], v[2:3]
	v_mov_b64_e32 v[66:67], v[2:3]
	v_mov_b64_e32 v[46:47], v[2:3]
	v_mov_b64_e32 v[70:71], v[2:3]
	v_mov_b64_e32 v[58:59], v[2:3]
	v_mov_b64_e32 v[74:75], v[2:3]
	v_mov_b64_e32 v[94:95], v[2:3]
	v_mov_b64_e32 v[78:79], v[2:3]
	v_mov_b64_e32 v[98:99], v[2:3]
	v_mov_b64_e32 v[82:83], v[2:3]
	v_mov_b64_e32 v[102:103], v[2:3]
	v_mov_b64_e32 v[86:87], v[2:3]
	v_mov_b64_e32 v[106:107], v[2:3]
	v_mov_b64_e32 v[90:91], v[2:3]
	s_xor_b64 s[60:61], s[58:59], -1
	v_mov_b32_e32 v174, v172
	v_mov_b32_e32 v175, v172
	s_mov_b32 s65, 0
	v_mov_b64_e32 v[36:37], v[0:1]
	v_mov_b64_e32 v[60:61], v[0:1]
	v_mov_b64_e32 v[40:41], v[0:1]
	v_mov_b64_e32 v[64:65], v[0:1]
	v_mov_b64_e32 v[44:45], v[0:1]
	v_mov_b64_e32 v[68:69], v[0:1]
	v_mov_b64_e32 v[56:57], v[0:1]
	v_mov_b64_e32 v[72:73], v[0:1]
	s_waitcnt vmcnt(0)
	v_mov_b64_e32 v[176:177], v[142:143]
	v_mov_b64_e32 v[180:181], v[140:141]
	v_mov_b64_e32 v[182:183], v[138:139]
	v_mov_b64_e32 v[184:185], v[136:137]
	v_mov_b64_e32 v[92:93], v[0:1]
	v_mov_b64_e32 v[76:77], v[0:1]
	v_mov_b64_e32 v[96:97], v[0:1]
	v_mov_b64_e32 v[80:81], v[0:1]
	v_mov_b64_e32 v[100:101], v[0:1]
	v_mov_b64_e32 v[84:85], v[0:1]
	v_mov_b64_e32 v[104:105], v[0:1]
	v_mov_b64_e32 v[88:89], v[0:1]
	s_mov_b32 s52, 0
	s_andn2_b64 vcc, exec, s[66:67]
	s_mov_b32 s53, s65
	s_cbranch_vccnz .LBB0_386
	s_branch .LBB0_382

; __device__ __forceinline__ float bf_lo(unsigned u) { return __uint_as_float(u << 16); }
; __device__ void ret_phase(const Params& p, unsigned char* ldsb, int lj, int half) {
;     ...
;                 for (int t = 0; t < 2; ++t) {
;                     const u32x4 vft = (u32x4){vv[2 * t].x, vv[2 * t].y, vv[2 * t + 1].x, vv[2 * t + 1].y};
;                     Vf[t] = __builtin_bit_cast(bf16x8, vft);
;                     const int j0 = 32 * t + 8 * g;
;                     const float base = __builtin_amdgcn_exp2f((dir == 0 ? (float)(63 - j0) : (float)j0) * l2g);
;                     const unsigned uu[4] = {vft.x, vft.y, vft.z, vft.w};
;                     unsigned oo[4];
; #pragma unroll
;                     for (int e2 = 0; e2 < 4; ++e2) oo[e2] = cvt_pk_bf16(bf_lo(uu[e2]) * (base * ge[2 * e2]), bf_hi(uu[e2]) * (base * ge[2 * e2 + 1]));
;                     Vs[t] = __builtin_bit_cast(bf16x8, (u32x4){oo[0], oo[1], oo[2], oo[3]});
;                 }
;                 const bool deadout = (lj == 1) && (s0 < 256);
;                 if (pass == 0 && !deadout) {
;                     f32x4 sc[2] = {(f32x4){0.f, 0.f, 0.f, 0.f}, (f32x4){0.f, 0.f, 0.f, 0.f}};
;                     const bf16_t* kp = Ks + (16 * jb + r) * KS_LD + 8 * g;
;                     const bf16_t* qp0 = Qs + (32 * ih + r) * QS_LD + 8 * g;
;                     bf16x8 ka[2], qb[2][2];
;                     ka[0] = *(const bf16x8*)kp; qb[0][0] = *(const bf16x8*)qp0; qb[0][1] = *(const bf16x8*)(qp0 + 16 * QS_LD);
; #pragma unroll
;                     for (int t = 0; t < 8; ++t) {
;                         if (t + 1 < 8) { ka[(t + 1) & 1] = *(const bf16x8*)(kp + 32 * (t + 1)); qb[(t + 1) & 1][0] = *(const bf16x8*)(qp0 + 32 * (t + 1)); qb[(t + 1) & 1][1] = *(const bf16x8*)(qp0 + 16 * QS_LD + 32 * (t + 1)); }
;                         sc[0] = __builtin_amdgcn_mfma_f32_16x16x32_bf16(ka[t & 1], qb[t & 1][0], sc[0], 0, 0, 0);
;                         sc[1] = __builtin_amdgcn_mfma_f32_16x16x32_bf16(ka[t & 1], qb[t & 1][1], sc[1], 0, 0, 0);
;                         __builtin_amdgcn_sched_barrier(0);
;                     }
; #pragma unroll
;                     for (int nt = 0; nt < 2; ++nt) { const int i = 32 * ih + 16 * nt + r; const int j0 = 16 * jb + 4 * g;
;                         float pv[4];
; #pragma unroll
;                         for (int jj = 0; jj < 4; ++jj) { const int df = j0 + jj - i;
.LBB0_404:
	v_sub_u32_e32 v108, 63, v173
	v_cndmask_b32_e64 v108, v173, v108, s[78:79]
	v_cvt_f32_i32_e32 v108, v108
	s_waitcnt lgkmcnt(0)
	v_add_u32_e32 v114, 32, v173
	v_and_b32_e32 v109, 0xffff0000, v140
	v_mul_f32_e32 v108, v191, v108
	v_exp_f32_e32 v111, v108
	v_lshlrev_b32_e32 v108, 16, v140
	v_sub_u32_e32 v115, 31, v173
	v_cndmask_b32_e64 v114, v114, v115, s[78:79]
	v_mul_f32_e32 v110, v192, v111
	v_mul_f32_e32 v112, v193, v111
	v_mul_f32_e32 v108, v110, v108
	v_mul_f32_e32 v109, v112, v109
	v_cvt_pk_bf16_f32 v108, v108, v109
	v_lshlrev_b32_e32 v109, 16, v141
	v_mul_f32_e32 v110, v194, v111
	v_cvt_f32_i32_e32 v114, v114
	v_mul_f32_e32 v109, v110, v109
	v_and_b32_e32 v110, 0xffff0000, v141
	v_mul_f32_e32 v112, v195, v111
	v_mul_f32_e32 v110, v112, v110
	v_cvt_pk_bf16_f32 v109, v109, v110
	v_lshlrev_b32_e32 v110, 16, v142
	v_mul_f32_e32 v112, v196, v111
	v_mul_f32_e32 v110, v112, v110
	v_and_b32_e32 v112, 0xffff0000, v142
	v_mul_f32_e32 v113, v197, v111
	v_mul_f32_e32 v114, v191, v114
	v_mul_f32_e32 v112, v113, v112
	v_exp_f32_e32 v115, v114
	v_cvt_pk_bf16_f32 v110, v110, v112
	v_lshlrev_b32_e32 v112, 16, v143
	v_mul_f32_e32 v113, v198, v111
	v_mul_f32_e32 v112, v113, v112
	v_and_b32_e32 v113, 0xffff0000, v143
	v_mul_f32_e32 v111, v199, v111
	v_mul_f32_e32 v111, v111, v113
	v_cvt_pk_bf16_f32 v111, v112, v111
	v_lshlrev_b32_e32 v112, 16, v136
	v_mul_f32_e32 v113, v192, v115
	v_mul_f32_e32 v112, v113, v112
	v_and_b32_e32 v113, 0xffff0000, v136
	v_mul_f32_e32 v114, v193, v115
	v_mul_f32_e32 v113, v114, v113
	v_cvt_pk_bf16_f32 v112, v112, v113
	v_lshlrev_b32_e32 v113, 16, v137
	v_mul_f32_e32 v114, v194, v115
	v_mul_f32_e32 v113, v114, v113
	v_and_b32_e32 v114, 0xffff0000, v137
	v_mul_f32_e32 v116, v195, v115
	v_mul_f32_e32 v114, v116, v114
	v_cvt_pk_bf16_f32 v113, v113, v114
	v_lshlrev_b32_e32 v114, 16, v138
	v_mul_f32_e32 v116, v196, v115
	s_cmpk_lt_u32 s53, 0x100
	v_mul_f32_e32 v114, v116, v114
	v_and_b32_e32 v116, 0xffff0000, v138
	v_mul_f32_e32 v117, v197, v115
	s_cselect_b64 s[88:89], -1, 0
	v_mul_f32_e32 v116, v117, v116
	v_cvt_pk_bf16_f32 v114, v114, v116
	v_lshlrev_b32_e32 v116, 16, v139
	v_mul_f32_e32 v117, v198, v115
	s_and_b64 s[74:75], s[6:7], s[88:89]
	v_mul_f32_e32 v116, v117, v116
	v_and_b32_e32 v117, 0xffff0000, v139
	v_mul_f32_e32 v115, v199, v115
	s_or_b64 s[4:5], s[78:79], s[74:75]
	v_mul_f32_e32 v115, v115, v117
	s_and_b64 vcc, exec, s[4:5]
	v_cvt_pk_bf16_f32 v115, v116, v115
	s_cbranch_vccnz .LBB0_406
	v_add_u32_e32 v116, s70, v1
	v_mul_lo_u32 v116, v116, s98
	v_lshlrev_b32_e32 v120, 1, v173
	v_add3_u32 v152, 0, v116, v120
	ds_read_b128 v[116:119], v152 offset:33792
	v_add_u32_e32 v153, s71, v1
	v_mul_lo_u32 v121, v153, s96
	v_add3_u32 v154, 0, v121, v120
	ds_read_b128 v[120:123], v154
	ds_read_b128 v[124:127], v152 offset:33856
	ds_read_b128 v[128:131], v154 offset:64
	ds_read_b128 v[132:135], v154 offset:8448
	ds_read_b128 v[144:147], v154 offset:8512
	s_waitcnt lgkmcnt(4)
	v_mfma_f32_16x16x32_bf16 v[120:123], v[116:119], v[120:123], 0
	s_waitcnt lgkmcnt(1)
	v_mfma_f32_16x16x32_bf16 v[116:119], v[116:119], v[132:135], 0
	v_mfma_f32_16x16x32_bf16 v[120:123], v[124:127], v[128:131], v[120:123]
	ds_read_b128 v[128:131], v152 offset:33920
	ds_read_b128 v[132:135], v154 offset:128
	ds_read_b128 v[148:151], v154 offset:8576
	s_waitcnt lgkmcnt(3)
	v_mfma_f32_16x16x32_bf16 v[116:119], v[124:127], v[144:147], v[116:119]
	s_waitcnt lgkmcnt(1)
	v_mfma_f32_16x16x32_bf16 v[120:123], v[128:131], v[132:135], v[120:123]
	ds_read_b128 v[124:127], v152 offset:33984
	ds_read_b128 v[132:135], v154 offset:192
	ds_read_b128 v[144:147], v154 offset:8640
	s_waitcnt lgkmcnt(3)
	v_mfma_f32_16x16x32_bf16 v[116:119], v[128:131], v[148:151], v[116:119]
	s_waitcnt lgkmcnt(1)
	v_mfma_f32_16x16x32_bf16 v[120:123], v[124:127], v[132:135], v[120:123]
	ds_read_b128 v[128:131], v152 offset:34048
	ds_read_b128 v[132:135], v154 offset:256
	ds_read_b128 v[148:151], v154 offset:8704
	s_waitcnt lgkmcnt(3)
	v_mfma_f32_16x16x32_bf16 v[116:119], v[124:127], v[144:147], v[116:119]
	s_waitcnt lgkmcnt(1)
	v_mfma_f32_16x16x32_bf16 v[120:123], v[128:131], v[132:135], v[120:123]
	ds_read_b128 v[124:127], v152 offset:34112
	ds_read_b128 v[132:135], v154 offset:320
	ds_read_b128 v[144:147], v154 offset:8768
	s_waitcnt lgkmcnt(3)
	v_mfma_f32_16x16x32_bf16 v[116:119], v[128:131], v[148:151], v[116:119]
	s_waitcnt lgkmcnt(1)
	v_mfma_f32_16x16x32_bf16 v[120:123], v[124:127], v[132:135], v[120:123]
	ds_read_b128 v[128:131], v152 offset:34176
	ds_read_b128 v[132:135], v154 offset:384
	ds_read_b128 v[148:151], v154 offset:8832
	s_waitcnt lgkmcnt(3)
	v_mfma_f32_16x16x32_bf16 v[116:119], v[124:127], v[144:147], v[116:119]
	s_waitcnt lgkmcnt(1)
	v_mfma_f32_16x16x32_bf16 v[120:123], v[128:131], v[132:135], v[120:123]
	ds_read_b128 v[124:127], v152 offset:34240
	ds_read_b128 v[132:135], v154 offset:448
	ds_read_b128 v[144:147], v154 offset:8896
	s_waitcnt lgkmcnt(3)
	v_mfma_f32_16x16x32_bf16 v[116:119], v[128:131], v[148:151], v[116:119]
	s_waitcnt lgkmcnt(1)
	v_mfma_f32_16x16x32_bf16 v[120:123], v[124:127], v[132:135], v[120:123]
	s_waitcnt lgkmcnt(0)
	v_mfma_f32_16x16x32_bf16 v[116:119], v[124:127], v[144:147], v[116:119]
	v_lshl_add_u32 v124, v200, 2, s70
	v_lshlrev_b32_e32 v125, 1, v124
	v_mul_lo_u32 v126, v153, s94
	s_nop 4
	v_mul_f32_e32 v120, v166, v120
	v_mul_f32_e32 v121, v167, v121
	v_cvt_pk_bf16_f32 v120, v120, v121
	v_mul_f32_e32 v122, v168, v122
	v_mul_f32_e32 v123, v169, v123
	v_cvt_pk_bf16_f32 v121, v122, v123
	v_add3_u32 v122, s51, v125, v126
	v_mul_f32_e32 v116, v170, v116
	v_mul_f32_e32 v117, v171, v117
	v_cvt_pk_bf16_f32 v116, v116, v117
	v_mul_f32_e32 v118, v250, v118
	v_mul_f32_e32 v119, v251, v119
	v_cvt_pk_bf16_f32 v117, v118, v119
	ds_write2st64_b64 v122, v[120:121], v[116:117] offset1:5
; template <bool WITH_B>
; __device__ __forceinline__ void scan_bc(const bf16_t* Ps, const bf16_t* Qp, int r, int g, const bf16x8 (&Vf)[2], const f32x4 (&S)[16], f32x4 (&o1)[4], f32x4 (&o2)[4]) {
;     constexpr int S0 = WITH_B ? 0 : 2;
;     u32x4 fb[2][4];
;     const bf16_t* pp = Ps + r * P_LD + 8 * g;
;     const bf16_t* qp = Qp + r * QP_LD + 8 * g;
;     if constexpr (WITH_B) {
; #pragma unroll
;         for (int nt = 0; nt < 4; ++nt) fb[0][nt] = *(const u32x4*)(pp + 16 * nt * P_LD);
;     } else {
; #pragma unroll
;         for (int nt = 0; nt < 4; ++nt) fb[0][nt] = *(const u32x4*)(qp + 16 * nt * QP_LD);
;     }
; #pragma unroll
;     for (int st = S0; st < 10; ++st) {
;         const int nx = st + 1;
;         if (nx < 2) {
; #pragma unroll
;             for (int nt = 0; nt < 4; ++nt) fb[nx & 1][nt] = *(const u32x4*)(pp + 16 * nt * P_LD + 32 * nx);
;         } else if (nx < 10) {
; #pragma unroll
;             for (int nt = 0; nt < 4; ++nt) fb[nx & 1][nt] = *(const u32x4*)(qp + 16 * nt * QP_LD + 32 * (nx - 2));
;         }
;         if (st < 2) {
; #pragma unroll
;             for (int nt = 0; nt < 4; ++nt) o1[nt] = __builtin_amdgcn_mfma_f32_16x16x32_bf16(Vf[st], __builtin_bit_cast(bf16x8, fb[st & 1][nt]), o1[nt], 0, 0, 0);
;         } else {
;             const int T = st - 2;
;             u32x4 aw; aw.x = cvt_pk_bf16(S[2 * T][0], S[2 * T][1]); aw.y = cvt_pk_bf16(S[2 * T][2], S[2 * T][3]); aw.z = cvt_pk_bf16(S[2 * T + 1][0], S[2 * T + 1][1]); aw.w = cvt_pk_bf16(S[2 * T + 1][2], S[2 * T + 1][3]);
;             const bf16x8 a = __builtin_bit_cast(bf16x8, aw);
; #pragma unroll
;             for (int nt = 0; nt < 4; ++nt) o2[nt] = __builtin_amdgcn_mfma_f32_16x16x32_bf16(a, __builtin_bit_cast(bf16x8, fb[st & 1][nt]), o2[nt], 0, 0, 0);
;         }
;         __builtin_amdgcn_sched_barrier(0);
;     }
; }
; __device__ void ret_phase(const Params& p, unsigned char* ldsb, int lj, int half) {
;     ...
;                 if (c + 1 < 36) issueK(c + 1);
;                 f32x4 o1[4], o2[4];
; #pragma unroll
;                 for (int nt = 0; nt < 4; ++nt) { o1[nt] = (f32x4){0.f, 0.f, 0.f, 0.f}; o2[nt] = (f32x4){0.f, 0.f, 0.f, 0.f}; }
;                 if (!deadout) {
;                     if (pass == 0) { __syncthreads(); scan_bc<true>(Ps, Qp, r, g, Vf, S, o1, o2); }
;                     else if (c > 0) scan_bc<false>(Ps, Qp, r, g, Vf, S, o1, o2);
;                 }
.LBB0_406:
	v_cndmask_b32_e64 v116, 0, 1, s[2:3]
	v_cmp_ne_u32_e64 s[4:5], 1, v116
	s_andn2_b64 vcc, exec, s[2:3]
	s_cbranch_vccnz .LBB0_416
.LBB0_415:
	s_cmpk_lt_i32 s11, 0x100
	s_cselect_b32 s2, s31, s50
	s_add_i32 s2, s2, s11
	s_ashr_i32 s3, s2, 31
	s_lshl_b64 s[2:3], s[2:3], 11
	s_add_u32 s2, s24, s2
	s_addc_u32 s3, s25, s3
	v_lshl_add_u64 v[28:29], s[2:3], 0, v[156:157]
	v_add_co_u32_e32 v20, vcc, 0x8000, v28
	s_nop 1
	v_addc_co_u32_e32 v21, vcc, 0, v29, vcc
	v_add_co_u32_e32 v30, vcc, 0x10000, v28
	global_load_dwordx4 v[12:15], v[28:29], off
	s_nop 0
	global_load_dwordx4 v[20:23], v[20:21], off
	v_addc_co_u32_e32 v31, vcc, 0, v29, vcc
	v_add_co_u32_e32 v48, vcc, 0x18000, v28
	s_nop 1
	v_addc_co_u32_e32 v49, vcc, 0, v29, vcc
	global_load_dwordx4 v[28:31], v[30:31], off
	s_nop 0
	global_load_dwordx4 v[48:51], v[48:49], off
.LBB0_416:
	s_xor_b64 s[74:75], s[74:75], -1
	v_mov_b32_e32 v116, 0
	v_cndmask_b32_e64 v117, 0, 1, s[74:75]
	v_cmp_ne_u32_e64 s[2:3], 1, v117
	s_andn2_b64 vcc, exec, s[74:75]
	s_cbranch_vccnz .LBB0_424
	s_mov_b64 s[74:75], -1
	s_and_b64 vcc, exec, s[60:61]
	s_cbranch_vccz .LBB0_422
	s_cmp_eq_u32 s65, 0
	s_cbranch_scc1 .LBB0_420
	v_mul_lo_u32 v116, v1, s98
	v_lshlrev_b32_e32 v117, 4, v200
	v_add3_u32 v208, s97, v116, v117
	ds_read_b128 v[116:119], v208
	ds_read_b128 v[120:123], v208 offset:64
	ds_read_b128 v[128:131], v208 offset:8704
	ds_read_b128 v[132:135], v208 offset:8768
	ds_read_b128 v[144:147], v208 offset:17408
	ds_read_b128 v[148:151], v208 offset:17472
	ds_read_b128 v[152:155], v208 offset:26112
	ds_read_b128 v[200:203], v208 offset:26176
	v_cvt_pk_bf16_f32 v124, v72, v73
	v_cvt_pk_bf16_f32 v125, v74, v75
	v_cvt_pk_bf16_f32 v126, v56, v57
	v_cvt_pk_bf16_f32 v127, v58, v59
	s_waitcnt lgkmcnt(7)
	v_mfma_f32_16x16x32_bf16 v[116:119], v[124:127], v[116:119], 0
	s_waitcnt lgkmcnt(5)
	v_mfma_f32_16x16x32_bf16 v[128:131], v[124:127], v[128:131], 0
	s_waitcnt lgkmcnt(3)
	v_mfma_f32_16x16x32_bf16 v[144:147], v[124:127], v[144:147], 0
	s_waitcnt lgkmcnt(1)
	v_mfma_f32_16x16x32_bf16 v[124:127], v[124:127], v[152:155], 0
	v_cvt_pk_bf16_f32 v152, v68, v69
	v_cvt_pk_bf16_f32 v153, v70, v71
	v_cvt_pk_bf16_f32 v154, v44, v45
	v_cvt_pk_bf16_f32 v155, v46, v47
	s_nop 0
	v_mfma_f32_16x16x32_bf16 v[116:119], v[152:155], v[120:123], v[116:119]
	v_mfma_f32_16x16x32_bf16 v[120:123], v[152:155], v[132:135], v[128:131]
	v_mfma_f32_16x16x32_bf16 v[128:131], v[152:155], v[148:151], v[144:147]
	ds_read_b128 v[132:135], v208 offset:128
	s_nop 1
	ds_read_b128 v[144:147], v208 offset:8832
	ds_read_b128 v[148:151], v208 offset:17536
	ds_read_b128 v[204:207], v208 offset:26240
	s_waitcnt lgkmcnt(4)
	v_mfma_f32_16x16x32_bf16 v[124:127], v[152:155], v[200:203], v[124:127]
	v_cvt_pk_bf16_f32 v152, v64, v65
	v_cvt_pk_bf16_f32 v153, v66, v67
	v_cvt_pk_bf16_f32 v154, v40, v41
	v_cvt_pk_bf16_f32 v155, v42, v43
	s_waitcnt lgkmcnt(3)
	v_mfma_f32_16x16x32_bf16 v[116:119], v[152:155], v[132:135], v[116:119]
	s_waitcnt lgkmcnt(2)
	v_mfma_f32_16x16x32_bf16 v[120:123], v[152:155], v[144:147], v[120:123]
	s_waitcnt lgkmcnt(1)
	v_mfma_f32_16x16x32_bf16 v[128:131], v[152:155], v[148:151], v[128:131]
	ds_read_b128 v[132:135], v208 offset:192
	ds_read_b128 v[144:147], v208 offset:8896
	ds_read_b128 v[148:151], v208 offset:17600
	ds_read_b128 v[200:203], v208 offset:26304
	s_waitcnt lgkmcnt(4)
	v_mfma_f32_16x16x32_bf16 v[124:127], v[152:155], v[204:207], v[124:127]
	v_cvt_pk_bf16_f32 v152, v60, v61
	v_cvt_pk_bf16_f32 v153, v62, v63
	v_cvt_pk_bf16_f32 v154, v36, v37
	v_cvt_pk_bf16_f32 v155, v38, v39
	s_waitcnt lgkmcnt(3)
	v_mfma_f32_16x16x32_bf16 v[116:119], v[152:155], v[132:135], v[116:119]
	s_waitcnt lgkmcnt(2)
	v_mfma_f32_16x16x32_bf16 v[120:123], v[152:155], v[144:147], v[120:123]
	s_waitcnt lgkmcnt(1)
	v_mfma_f32_16x16x32_bf16 v[128:131], v[152:155], v[148:151], v[128:131]
	ds_read_b128 v[132:135], v208 offset:256
	ds_read_b128 v[144:147], v208 offset:8960
	ds_read_b128 v[148:151], v208 offset:17664
	ds_read_b128 v[204:207], v208 offset:26368
	s_waitcnt lgkmcnt(4)
	v_mfma_f32_16x16x32_bf16 v[124:127], v[152:155], v[200:203], v[124:127]
	v_cvt_pk_bf16_f32 v152, v92, v93
	v_cvt_pk_bf16_f32 v153, v94, v95
	v_cvt_pk_bf16_f32 v154, v76, v77
	v_cvt_pk_bf16_f32 v155, v78, v79
	s_waitcnt lgkmcnt(3)
	v_mfma_f32_16x16x32_bf16 v[116:119], v[152:155], v[132:135], v[116:119]
	s_waitcnt lgkmcnt(2)
	v_mfma_f32_16x16x32_bf16 v[120:123], v[152:155], v[144:147], v[120:123]
	s_waitcnt lgkmcnt(1)
	v_mfma_f32_16x16x32_bf16 v[128:131], v[152:155], v[148:151], v[128:131]
	ds_read_b128 v[132:135], v208 offset:320
	ds_read_b128 v[144:147], v208 offset:9024
	ds_read_b128 v[148:151], v208 offset:17728
	ds_read_b128 v[200:203], v208 offset:26432
	s_waitcnt lgkmcnt(4)
	v_mfma_f32_16x16x32_bf16 v[124:127], v[152:155], v[204:207], v[124:127]
	v_cvt_pk_bf16_f32 v152, v96, v97
	v_cvt_pk_bf16_f32 v153, v98, v99
	v_cvt_pk_bf16_f32 v154, v80, v81
	v_cvt_pk_bf16_f32 v155, v82, v83
	s_waitcnt lgkmcnt(3)
	v_mfma_f32_16x16x32_bf16 v[116:119], v[152:155], v[132:135], v[116:119]
	s_waitcnt lgkmcnt(2)
	v_mfma_f32_16x16x32_bf16 v[120:123], v[152:155], v[144:147], v[120:123]
	s_waitcnt lgkmcnt(1)
	v_mfma_f32_16x16x32_bf16 v[128:131], v[152:155], v[148:151], v[128:131]
	ds_read_b128 v[132:135], v208 offset:384
	ds_read_b128 v[144:147], v208 offset:9088
	ds_read_b128 v[148:151], v208 offset:17792
	ds_read_b128 v[204:207], v208 offset:26496
	s_waitcnt lgkmcnt(4)
	v_mfma_f32_16x16x32_bf16 v[124:127], v[152:155], v[200:203], v[124:127]
	v_cvt_pk_bf16_f32 v152, v100, v101
	v_cvt_pk_bf16_f32 v153, v102, v103
	v_cvt_pk_bf16_f32 v154, v84, v85
	v_cvt_pk_bf16_f32 v155, v86, v87
	s_waitcnt lgkmcnt(3)
	v_mfma_f32_16x16x32_bf16 v[116:119], v[152:155], v[132:135], v[116:119]
	s_waitcnt lgkmcnt(2)
	v_mfma_f32_16x16x32_bf16 v[120:123], v[152:155], v[144:147], v[120:123]
	ds_read_b128 v[132:135], v208 offset:448
	ds_read_b128 v[144:147], v208 offset:9152
	ds_read_b128 v[200:203], v208 offset:17856
	ds_read_b128 v[226:229], v208 offset:26560
	s_waitcnt lgkmcnt(5)
	v_mfma_f32_16x16x32_bf16 v[128:131], v[152:155], v[148:151], v[128:131]
	s_waitcnt lgkmcnt(4)
	v_mfma_f32_16x16x32_bf16 v[124:127], v[152:155], v[204:207], v[124:127]
	v_cvt_pk_bf16_f32 v204, v104, v105
	v_cvt_pk_bf16_f32 v205, v106, v107
	v_cvt_pk_bf16_f32 v206, v88, v89
	v_cvt_pk_bf16_f32 v207, v90, v91
	s_waitcnt lgkmcnt(3)
	v_mfma_f32_16x16x32_bf16 v[152:155], v[204:207], v[132:135], v[116:119]
	s_waitcnt lgkmcnt(2)
	v_mfma_f32_16x16x32_bf16 v[148:151], v[204:207], v[144:147], v[120:123]
	s_waitcnt lgkmcnt(1)
	v_mfma_f32_16x16x32_bf16 v[128:131], v[204:207], v[200:203], v[128:131]
	s_waitcnt lgkmcnt(0)
	v_mfma_f32_16x16x32_bf16 v[124:127], v[204:207], v[226:229], v[124:127]
	s_branch .LBB0_421

; __device__ void ret_phase(const Params& p, unsigned char* ldsb, int lj, int half) {
;     ...
;             auto issueVY = [&](int c) { const char* bv = (const char*)(Vg + (size_t)lrow(spos(c)) * 2048 + h * 512 + sl * 128);
; #pragma unroll
;                 for (int k = 0; k < 2; ++k) sv[k] = *(const u32x4*)(bv + (size_t)k * 131072 + vo_v);
;                 if (pass == 1) { const char* by = (const char*)(Y + (size_t)grow(spos(c)) * 2048 + h * 512 + sl * 128 + 16 * w);
; #pragma unroll
;                     for (int nt = 0; nt < 4; ++nt) yold[nt] = *(const u32x2*)(by + (size_t)nt * 65536 + vo_y); } };
;     ...
;                 if (c + 1 < 36) issueVY(c + 1);
.LBB0_424:
	s_and_b64 vcc, exec, s[4:5]
	s_cbranch_vccnz .LBB0_436
.LBB0_433:
	s_cmpk_lt_i32 s11, 0x100
	s_cselect_b32 s4, s31, s50
	s_add_i32 s4, s4, s11
	s_ashr_i32 s5, s4, 31
	s_lshl_b64 s[4:5], s[4:5], 12
	s_add_u32 s4, s0, s4
	s_addc_u32 s5, s1, s5
	v_lshl_add_u64 v[32:33], s[4:5], 0, v[158:159]
	v_add_co_u32_e32 v52, vcc, 0x20000, v32
	v_mov_b64_e32 v[142:143], v[176:177]
	s_nop 0
	v_addc_co_u32_e32 v53, vcc, 0, v33, vcc
	global_load_dwordx4 v[32:35], v[32:33], off
	s_nop 0
	global_load_dwordx4 v[52:55], v[52:53], off
	s_andn2_b64 vcc, exec, s[78:79]
	v_mov_b64_e32 v[140:141], v[180:181]
	v_mov_b64_e32 v[138:139], v[182:183]
	v_mov_b64_e32 v[136:137], v[184:185]
	s_cbranch_vccnz .LBB0_435
	s_cmp_lt_u32 s52, 3
	s_cselect_b32 s4, s64, s36
	s_add_i32 s4, s4, s65
	s_add_i32 s4, s4, 64
	s_ashr_i32 s5, s4, 31
	s_lshl_b64 s[4:5], s[4:5], 12
	s_add_u32 s4, s28, s4
	s_addc_u32 s5, s29, s5
	v_lshl_add_u64 v[136:137], s[4:5], 0, v[160:161]
	v_add_co_u32_e32 v138, vcc, 0x10000, v136
	s_nop 1
	v_addc_co_u32_e32 v139, vcc, 0, v137, vcc
	v_add_co_u32_e32 v140, vcc, 0x20000, v136
	s_nop 1
	v_addc_co_u32_e32 v141, vcc, 0, v137, vcc
	v_add_co_u32_e32 v142, vcc, 0x30000, v136
	s_nop 1
	v_addc_co_u32_e32 v143, vcc, 0, v137, vcc
	global_load_dwordx2 v[136:137], v[136:137], off
	s_nop 0
	global_load_dwordx2 v[138:139], v[138:139], off
	s_nop 0
	global_load_dwordx2 v[140:141], v[140:141], off
	s_nop 0
	global_load_dwordx2 v[142:143], v[142:143], off

; __device__ __forceinline__ unsigned cvt_pk_bf16(float lo, float hi) { unsigned r; asm("v_cvt_pk_bf16_f32 %0, %1, %2" : "=v"(r) : "v"(lo), "v"(hi)); return r; }
; __device__ __forceinline__ float bf_lo(unsigned u) { return __uint_as_float(u << 16); }
; __device__ __forceinline__ float bf_hi(unsigned u) { return __uint_as_float(u & 0xffff0000u); }
; __device__ void ret_phase(const Params& p, unsigned char* ldsb, int lj, int half) {
;     ...
;                 if (!deadout)
; #pragma unroll
;                 for (int nt = 0; nt < 4; ++nt) { const int i = 16 * nt + r;
;                     const float qd = __builtin_amdgcn_exp2f((dir == 0 ? (float)(i + 1) : (float)(64 - i)) * l2g);
;                     f32x4 yv = o1[nt] + o2[nt] * qd;
;                     bf16_t* yp = (bf16_t*)((char*)(Y + (size_t)grow0 * 2048 + h * 512 + sl * 128 + 16 * w) + (size_t)nt * 65536 + vo_y);
;                     if (pass == 1) { yv[0] += bf_lo(yo[nt].x); yv[1] += bf_hi(yo[nt].x); yv[2] += bf_lo(yo[nt].y); yv[3] += bf_hi(yo[nt].y); }
;                     u32x2 o; o.x = cvt_pk_bf16(yv[0], yv[1]); o.y = cvt_pk_bf16(yv[2], yv[3]);
;                     *(u32x2*)yp = o; }
.LBB0_437:
	v_cndmask_b32_e64 v3, 0, 1, s[78:79]
	v_cmp_ne_u32_e64 s[2:3], 1, v3
	s_andn2_b64 vcc, exec, s[78:79]
	v_mov_b32_e32 v2, v252
	v_pk_fma_f32 v[108:109], v[2:3], v[154:155], v[146:147] op_sel_hi:[0,1,1]
	v_pk_fma_f32 v[110:111], v[2:3], v[152:153], v[144:145] op_sel_hi:[0,1,1]
	s_cbranch_vccnz .LBB0_439
	v_lshlrev_b32_e32 v2, 16, v184
	v_and_b32_e32 v3, 0xffff0000, v184
	v_pk_add_f32 v[110:111], v[110:111], v[2:3]
	v_lshlrev_b32_e32 v2, 16, v185
	v_and_b32_e32 v3, 0xffff0000, v185
	v_pk_add_f32 v[108:109], v[108:109], v[2:3]
.LBB0_439:
	v_cvt_pk_bf16_f32 v110, v110, v111
	s_nop 0
	v_cvt_pk_bf16_f32 v111, v108, v109
	s_and_b64 s[4:5], s[88:89], exec
	s_cselect_b32 s4, s64, s36
	s_add_i32 s4, s4, s53
	s_ashr_i32 s5, s4, 31
	s_lshl_b64 s[4:5], s[4:5], 12
	v_lshl_add_u64 v[2:3], v[162:163], 0, s[4:5]
	global_store_dwordx2 v[2:3], v[110:111], off
	v_mov_b32_e32 v110, v253
	s_and_b64 vcc, exec, s[2:3]
	v_pk_fma_f32 v[108:109], v[110:111], v[150:151], v[134:135] op_sel_hi:[0,1,1]
	v_pk_fma_f32 v[110:111], v[110:111], v[148:149], v[132:133] op_sel_hi:[0,1,1]
	s_cbranch_vccnz .LBB0_441
	v_lshlrev_b32_e32 v112, 16, v182
	v_and_b32_e32 v113, 0xffff0000, v182
	v_pk_add_f32 v[110:111], v[110:111], v[112:113]
	v_lshlrev_b32_e32 v112, 16, v183
	v_and_b32_e32 v113, 0xffff0000, v183
	v_pk_add_f32 v[108:109], v[108:109], v[112:113]
.LBB0_441:
	v_cvt_pk_bf16_f32 v110, v110, v111
	s_nop 0
	v_cvt_pk_bf16_f32 v111, v108, v109
	v_add_co_u32_e32 v108, vcc, 0x10000, v2
	s_nop 1
	v_addc_co_u32_e32 v109, vcc, 0, v3, vcc
	global_store_dwordx2 v[108:109], v[110:111], off
	s_and_b64 vcc, exec, s[2:3]
	v_mov_b32_e32 v110, v209
	v_pk_fma_f32 v[108:109], v[110:111], v[130:131], v[122:123] op_sel_hi:[0,1,1]
	v_pk_fma_f32 v[110:111], v[110:111], v[128:129], v[120:121] op_sel_hi:[0,1,1]
	s_cbranch_vccnz .LBB0_443
	v_lshlrev_b32_e32 v112, 16, v180
	v_and_b32_e32 v113, 0xffff0000, v180
	v_pk_add_f32 v[110:111], v[110:111], v[112:113]
	v_lshlrev_b32_e32 v112, 16, v181
	v_and_b32_e32 v113, 0xffff0000, v181
	v_pk_add_f32 v[108:109], v[108:109], v[112:113]
.LBB0_443:
	v_cvt_pk_bf16_f32 v110, v110, v111
	v_cvt_pk_bf16_f32 v111, v108, v109
	v_add_co_u32_e32 v108, vcc, 0x20000, v2
	v_mov_b32_e32 v112, v225
	s_nop 0
	v_addc_co_u32_e32 v109, vcc, 0, v3, vcc
	global_store_dwordx2 v[108:109], v[110:111], off
	v_pk_fma_f32 v[108:109], v[112:113], v[126:127], v[118:119] op_sel_hi:[0,1,1]
	s_and_b64 vcc, exec, s[2:3]
	v_pk_fma_f32 v[110:111], v[112:113], v[124:125], v[116:117] op_sel_hi:[0,1,1]
	s_cbranch_vccnz .LBB0_445
	v_lshlrev_b32_e32 v112, 16, v176
	v_and_b32_e32 v113, 0xffff0000, v176
	v_pk_add_f32 v[110:111], v[110:111], v[112:113]
	v_lshlrev_b32_e32 v112, 16, v177
	v_and_b32_e32 v113, 0xffff0000, v177
	v_pk_add_f32 v[108:109], v[108:109], v[112:113]
